# ret scan pad 32 + hg2 scan full pad 32 (Q/K/logf stride 288, V^T and P stride 160)
# speedup vs baseline: 1.0066x; 1.0028x over previous
; #define LAS __attribute__((address_space(3)))
; __device__ __forceinline__ void mixer_hg2(const Args& a, Frame& F, bool ctx_out) {
;     ...
;     const int lane = F.lane, w = F.wave, tid = F.tid, g = lane >> 4, i = lane & 15;
;     const int rg = w >> 1, cg = w & 1, nq0 = 16 * rg;
;     LAS unsigned char* const L = F.lds;
;     const bf16* act = (const bf16*)(a.ws + WS_ACT);
;     mx_bf16x8 bt0, bt1;
; #pragma unroll
;     for (int j = 0; j < 8; ++j) { bt0[j] = (8 * g + j <= i) ? (short)0x3F80 : (short)0; bt1[j] = (8 * g + j <= 16 + i) ? (short)0x3F80 : (short)0; }
;     for (int task = F.vcu; task < BATCH * NH * 2 * NEB; task += F.G) {
;         const int eb = task % NEB, dir = (task / NEB) & 1, h = (task / (2 * NEB)) % NH, b = task / (2 * NEB * NH);
;         bf16* O = (bf16*)(a.ws + (dir ? WS_OB : WS_OF));
;         const bf16* src0 = act;
;         const bf16* src1 = act + (size_t)(2 + 2 * dir) * ACT_STRIDE;
;         const bf16* src2 = act + (size_t)(1 + 2 * dir) * ACT_STRIDE;
;         const bf16* srcv = act + (size_t)5 * ACT_STRIDE;
;         const int vrow = tid & 63, vcc = tid >> 6, vs = dir ? 63 - vrow : vrow;
;         f32x4 accS[4];
; #pragma unroll
;         for (int te = 0; te < 4; ++te) accS[te] = ZERO4;
;         constexpr int PF = MX_PF_HG;
;         static_assert(NCH % PF == 0, "prefetch depth must divide the chunk count");
;         v4u rq[PF][3][2]; v4u rv[PF];
.LBB0_507:
	s_andn2_b64 vcc, exec, s[8:9]
	s_cbranch_vccnz .LBB0_570
	s_getreg_b32 s6, hwreg(HW_REG_HW_ID, 0, 6)
	s_lshl_b32 s6, s6, 2
	s_add_i32 s6, s6, 0
	s_add_i32 s6, s6, 0x20540
	v_mov_b32_e32 v0, s6
	ds_read_b32 v0, v0
	v_readlane_b32 s8, v254, 25
	v_mbcnt_lo_u32_b32 v3, -1, 0
	v_mbcnt_hi_u32_b32 v3, -1, v3
	v_readlane_b32 s9, v254, 26
	v_mov_b32_e32 v2, v1
	s_waitcnt lgkmcnt(0)
	v_readfirstlane_b32 s6, v0
	s_andn2_b64 vcc, exec, s[8:9]
	s_nop 0
	v_lshl_add_u32 v0, s6, 6, v3
	s_nop 0
	v_readfirstlane_b32 s6, v0
	s_cbranch_vccnz .LBB0_524
	s_waitcnt vmcnt(0)
	v_mov_b64_e32 v[4:5], s[0:1]
	flat_load_dwordx2 v[14:15], v[4:5] offset:152
	v_and_b32_e32 v18, 15, v0
	v_bfe_u32 v19, v0, 4, 2
	v_or_b32_e32 v11, 16, v18
	v_lshlrev_b32_e32 v12, 3, v19
	v_lshlrev_b32_e32 v8, 4, v0
	v_cmp_gt_u32_e32 vcc, v12, v11
	v_mov_b32_e32 v31, 0x3f80
	v_lshlrev_b32_e32 v6, 3, v0
	v_bfe_u32 v9, v0, 2, 2
	v_lshrrev_b32_e32 v10, 1, v0
	v_and_b32_e32 v186, 0xf0, v8
	v_cndmask_b32_e64 v8, v31, 0, vcc
	v_cmp_lt_u32_e32 vcc, v12, v11
	v_and_b32_e32 v184, 0x78, v6
	v_and_or_b32 v6, v10, 24, v9
	v_cndmask_b32_e32 v9, 0, v31, vcc
	v_cmp_gt_u32_e32 vcc, v12, v18
	v_and_b32_e32 v185, 63, v0
	s_ashr_i32 s6, s6, 6
	v_ashrrev_i32_e32 v7, 3, v0
	v_cndmask_b32_e64 v10, v31, 0, vcc
	v_cmp_lt_u32_e32 vcc, v12, v18
	v_or_b32_e32 v21, 2, v12
	v_and_b32_e32 v16, -8, v7
	s_lshl_b32 s9, s6, 5
	v_lshlrev_b32_e32 v7, 3, v185
	v_cndmask_b32_e32 v13, 0, v31, vcc
	v_or_b32_e32 v20, 3, v12
	v_cmp_gt_u32_e32 vcc, v21, v11
	v_and_or_b32 v27, v7, 16, s9
	v_and_b32_e32 v28, 8, v7
	s_mov_b32 s10, 0x5040100
	v_cndmask_b32_e64 v7, v31, 0, vcc
	v_cmp_gt_u32_e32 vcc, v20, v11
	v_mul_u32_u24_e32 v26, 0x120, v6
	v_perm_b32 v6, v9, v8, s10
	v_cndmask_b32_e64 v8, v31, 0, vcc
	v_cmp_gt_u32_e32 vcc, v21, v18
	v_or_b32_e32 v23, 4, v12
	v_or_b32_e32 v22, 5, v12
	v_cndmask_b32_e64 v9, v31, 0, vcc
	v_cmp_gt_u32_e32 vcc, v20, v18
	v_perm_b32 v10, v13, v10, s10
	v_or_b32_e32 v25, 6, v12
	v_cndmask_b32_e64 v13, v31, 0, vcc
	v_cmp_gt_u32_e32 vcc, v23, v11
	v_or_b32_e32 v24, 7, v12
	v_readlane_b32 s24, v254, 62
	v_cndmask_b32_e64 v20, v31, 0, vcc
	v_cmp_gt_u32_e32 vcc, v22, v11
	s_lshl_b32 s8, s6, 3
	s_add_i32 s6, s9, s24
	v_cndmask_b32_e64 v21, v31, 0, vcc
	v_cmp_gt_u32_e32 vcc, v23, v18
	s_add_i32 s7, s9, 0
	v_add3_u32 v26, 0, v26, v27
	v_cndmask_b32_e64 v23, v31, 0, vcc
	v_cmp_gt_u32_e32 vcc, v22, v18
	v_add_u32_e32 v27, s6, v12
	v_bfi_b32 v229, -16, s8, v0
	v_cndmask_b32_e64 v22, v31, 0, vcc
	v_cmp_gt_u32_e32 vcc, v25, v11
	s_movk_i32 s25, 0x120
	v_perm_b32 v7, v8, v7, s10
	v_cndmask_b32_e64 v29, v31, 0, vcc
	v_cmp_gt_u32_e32 vcc, v24, v11
	v_perm_b32 v8, v21, v20, s10
	v_and_b32_e32 v232, 48, v0
	v_cndmask_b32_e64 v30, v31, 0, vcc
	v_cmp_gt_u32_e32 vcc, v25, v18
	v_ashrrev_i32_e32 v237, 4, v0
	v_add_u32_e32 v0, 0x200, v0
	v_cndmask_b32_e64 v25, v31, 0, vcc
	v_cmp_gt_u32_e32 vcc, v24, v18
	v_perm_b32 v11, v13, v9, s10
	v_perm_b32 v9, v30, v29, s10
	v_cndmask_b32_e64 v24, v31, 0, vcc
	v_add_u32_e32 v31, s7, v12
	s_mov_b64 s[6:7], 0xd000000
	s_waitcnt vmcnt(0) lgkmcnt(0)
	v_lshl_add_u64 v[188:189], v[14:15], 0, s[6:7]
	s_mov_b64 s[6:7], 0x22400000
	v_lshl_add_u64 v[190:191], v[14:15], 0, s[6:7]
	v_mul_lo_u32 v14, v229, s25
	v_add_u32_e32 v230, 0, v14
	s_and_b32 s6, s9, 32
	v_lshlrev_b32_e32 v14, 2, v19
	v_or_b32_e32 v19, s6, v14
	v_or_b32_e32 v21, 2, v19
	v_cmp_gt_i32_e64 s[12:13], v21, v229
	v_or_b32_e32 v21, 3, v19
	v_cmp_gt_i32_e64 s[14:15], v21, v229
	v_lshlrev_b32_e32 v21, 7, v229
	v_sub_u32_e32 v233, v230, v21
	v_add_u32_e32 v233, 0x10000, v233
	v_or_b32_e32 v21, 17, v19
	s_movk_i32 s7, 0xa0
	v_perm_b32 v12, v22, v23, s10
	v_perm_b32 v13, v24, v25, s10
	v_or_b32_e32 v20, 16, v19
	v_cmp_gt_i32_e64 s[8:9], v19, v229
	v_cmp_lt_i32_e64 s[10:11], v19, v229
	v_lshlrev_b32_e32 v234, 1, v19
	v_cmp_gt_i32_e64 s[18:19], v21, v229
	v_or_b32_e32 v21, 18, v19
	v_or_b32_e32 v19, 19, v19
	v_ashrrev_i32_e32 v238, 4, v0
	v_mul_lo_u32 v0, v16, s7
	v_lshlrev_b32_e32 v187, 1, v185
	v_ashrrev_i32_e32 v17, 31, v16
	v_or_b32_e32 v15, s6, v18
	v_cmp_gt_i32_e64 s[22:23], v19, v229
	v_add_u32_e32 v241, 0, v0
	v_mul_u32_u24_e32 v19, 0x120, v18
	v_mad_u32_u24 v18, v18, s7, 0
	v_mov_b32_e32 v0, s24
	v_mov_b32_e32 v3, v2
	v_mov_b32_e32 v4, v2
	v_mov_b32_e32 v5, v2
	v_xor_b32_e32 v228, 0x7e, v187
	v_mad_u32_u24 v231, v15, s25, 0
	v_cmp_gt_i32_e64 s[16:17], v20, v229
	v_cmp_gt_i32_e64 s[20:21], v21, v229
	v_lshlrev_b32_e32 v235, 1, v20
	v_sub_u32_e32 v236, 63, v229
	v_sub_u32_e32 v239, 63, v237
	v_sub_u32_e32 v240, 63, v238
	v_mad_u32_u24 v242, v15, s25, v0
	v_mad_u32_u24 v243, v15, s7, 0
	v_lshlrev_b64 v[192:193], 1, v[16:17]
	s_lshl_b32 s28, s6, 1
	v_lshlrev_b32_e32 v0, 1, v14
	v_add_u32_e32 v244, v18, v232
	v_add_u32_e32 v245, v26, v28
	v_add_u32_e32 v246, v27, v19
	v_add_u32_e32 v247, v31, v19
	v_readlane_b32 s6, v254, 4
	s_branch .LBB0_511
; #define LAS __attribute__((address_space(3)))
; __device__ __forceinline__ void mixer_hg2(const Args& a, Frame& F, bool ctx_out) {
;     ...
;             f32x4 fe, fu;
;             {
;                 unsigned one2_ = 0x3F803F80u; asm volatile("" : "+v"(one2_));
;                 typedef unsigned u4_ __attribute__((ext_vector_type(4)));
;                 const mx_bf16x8 ones = __builtin_bit_cast(mx_bf16x8, (u4_){one2_, one2_, one2_, one2_});
;                 const mx_bf16x8 a0 = frag_tr(L + 2 * IMG, QS, 0, 16 * w, lane), a1 = frag_tr(L + 2 * IMG, QS, 32, 16 * w, lane);
;                 const f32x4 z = ZERO4;
;                 f32x4 ct[4];
;                 ct[0] = MX_MFMA(a0, bt0, z); ct[1] = MX_MFMA(a0, bt1, z);
;                 const f32x4 cref = MX_MFMA(a0, ones, z);
;                 ct[2] = MX_MFMA(a1, bt0, cref); ct[3] = MX_MFMA(a1, bt1, cref);
;                 const f32x4 cend = MX_MFMA(a1, ones, cref);
;                 fe = (f32x4){__expf(cend[0]), __expf(cend[1]), __expf(cend[2]), __expf(cend[3])};
;                 fu = (f32x4){__expf(cend[0] - cref[0]), __expf(cend[1] - cref[1]), __expf(cend[2] - cref[2]), __expf(cend[3] - cref[3])};
;                 const f32x4 fs = {__expf(cref[0]), __expf(cref[1]), __expf(cref[2]), __expf(cref[3])};
; #pragma unroll
;                 for (int te = 0; te < 4; ++te) { const f32x4 s = accS[te] * fs; v2u sw; sw.x = pk2(s[0], s[1]); sw.y = pk2(s[2], s[3]);
;                     *(LAS v2u*)(L + O_ST + (16 * te + i) * QS + (16 * w + 4 * g) * 2) = sw; }
; #pragma unroll
;                 for (int t = 0; t < 4; ++t) {
;                     LAS unsigned char* pq = L + (16 * t + i) * QS + (16 * w + 4 * g) * 2;
;                     const v2u qw = *(const LAS v2u*)pq, kw = *(const LAS v2u*)(pq + IMG);
;                     const f32x4 dd = ct[t] - cref;
;                     const f32x4 tt = (f32x4){__builtin_amdgcn_fmed3f(dd[0], -80.f, 80.f), __builtin_amdgcn_fmed3f(dd[1], -80.f, 80.f), __builtin_amdgcn_fmed3f(dd[2], -80.f, 80.f), __builtin_amdgcn_fmed3f(dd[3], -80.f, 80.f)} * 1.4426950408889634f;
;                     const f32x4 e1 = {__builtin_amdgcn_exp2f(tt[0]), __builtin_amdgcn_exp2f(tt[1]), __builtin_amdgcn_exp2f(tt[2]), __builtin_amdgcn_exp2f(tt[3])};
;                     const f32x4 e2 = {__builtin_amdgcn_rcpf(e1[0]), __builtin_amdgcn_rcpf(e1[1]), __builtin_amdgcn_rcpf(e1[2]), __builtin_amdgcn_rcpf(e1[3])};
.LBB0_510:
	s_waitcnt vmcnt(4)
	ds_write_b128 v251, v[94:97]
	s_waitcnt vmcnt(3)
	ds_write_b128 v251, v[98:101] offset:18432
	ds_write_b128 v251, v[102:105] offset:36864
	ds_write_b128 v250, v[110:113]
	s_waitcnt vmcnt(2)
	ds_write_b128 v250, v[106:109] offset:18432
	s_waitcnt vmcnt(1)
	ds_write_b128 v250, v[114:117] offset:36864
	s_waitcnt vmcnt(0)
	ds_write_b16 v249, v118 offset:55296
	ds_write_b16_d16_hi v249, v118 offset:55456
	ds_write_b16 v249, v119 offset:55616
	ds_write_b16_d16_hi v249, v119 offset:55776
	ds_write_b16 v249, v120 offset:55936
	ds_write_b16_d16_hi v249, v120 offset:56096
	ds_write_b16 v249, v121 offset:56256
	ds_write_b16_d16_hi v249, v121 offset:56416
	v_mov_b32_e32 v14, 0x3f803f80
	s_waitcnt lgkmcnt(0)
	s_barrier
	ds_read_b64_tr_b16 v[18:19], v245 offset:36864
	ds_read_b64_tr_b16 v[20:21], v245 offset:38016
	ds_read_b64_tr_b16 v[30:31], v245 offset:46080
	ds_read_b64_tr_b16 v[32:33], v245 offset:47232
	v_mov_b32_e32 v15, v14
	v_mov_b32_e32 v16, v14
	v_mov_b32_e32 v17, v14
	s_waitcnt lgkmcnt(2)
	v_mfma_f32_16x16x32_bf16 v[34:37], v[18:21], v[10:13], v[2:5]
	v_add_u32_e32 v54, v231, v232
	s_and_b64 s[24:25], s[24:25], exec
	s_cselect_b32 s24, 0xfc0, 0
	v_mfma_f32_16x16x32_bf16 v[14:17], v[18:21], v[14:17], v[2:5]
	s_or_b32 s7, s24, s7
	v_mfma_f32_16x16x32_bf16 v[26:29], v[18:21], v[6:9], v[2:5]
	s_waitcnt lgkmcnt(0)
	v_mfma_f32_16x16x32_bf16 v[22:25], v[30:33], v[10:13], v[14:17]
	s_nop 3
	v_mul_f32_e32 v18, 0x3fb8aa3b, v14
	v_mul_f32_e32 v19, 0x3fb8aa3b, v16
	v_exp_f32_e32 v38, v18
	v_mul_f32_e32 v18, 0x3fb8aa3b, v15
	v_exp_f32_e32 v40, v19
	v_mul_f32_e32 v19, 0x3fb8aa3b, v17
	v_exp_f32_e32 v41, v19
	v_exp_f32_e32 v39, v18
	v_mfma_f32_16x16x32_bf16 v[18:21], v[30:33], v[6:9], v[14:17]
	v_sub_f32_e32 v37, v37, v17
	v_pk_mul_f32 v[30:31], v[218:219], v[40:41]
	v_pk_mul_f32 v[32:33], v[214:215], v[38:39]
	v_sub_f32_e32 v36, v36, v16
	v_cvt_pk_bf16_f32 v32, v32, v33
	v_cvt_pk_bf16_f32 v33, v30, v31
	ds_write_b64 v246, v[32:33]
	v_pk_mul_f32 v[30:31], v[212:213], v[40:41]
	v_pk_mul_f32 v[32:33], v[210:211], v[38:39]
	v_sub_f32_e32 v35, v35, v15
	v_cvt_pk_bf16_f32 v32, v32, v33
	v_cvt_pk_bf16_f32 v33, v30, v31
	ds_write_b64 v246, v[32:33] offset:4608
	v_pk_mul_f32 v[30:31], v[208:209], v[40:41]
	v_pk_mul_f32 v[32:33], v[206:207], v[38:39]
	v_sub_f32_e32 v34, v34, v14
	v_cvt_pk_bf16_f32 v32, v32, v33
	v_cvt_pk_bf16_f32 v33, v30, v31
	v_med3_f32 v34, v34, s95, v182
	v_med3_f32 v35, v35, s95, v182
	v_med3_f32 v36, v36, s95, v182
	v_med3_f32 v37, v37, s95, v182
	ds_write_b64 v246, v[32:33] offset:9216
	v_pk_mul_f32 v[30:31], v[204:205], v[40:41]
	v_pk_mul_f32 v[32:33], v[202:203], v[38:39]
	v_pk_mul_f32 v[36:37], v[36:37], s[56:57] op_sel_hi:[1,0]
	v_pk_mul_f32 v[34:35], v[34:35], s[56:57] op_sel_hi:[1,0]
	v_cvt_pk_bf16_f32 v32, v32, v33
	v_cvt_pk_bf16_f32 v33, v30, v31
	v_exp_f32_e32 v34, v34
	v_exp_f32_e32 v35, v35
	v_exp_f32_e32 v36, v36
	v_exp_f32_e32 v37, v37
	ds_write_b64 v246, v[32:33] offset:13824
	ds_read_b64 v[30:31], v247
	ds_read_b64 v[32:33], v247 offset:18432
	v_sub_f32_e32 v29, v29, v17
	v_sub_f32_e32 v28, v28, v16
	v_sub_f32_e32 v27, v27, v15
	v_sub_f32_e32 v26, v26, v14
	v_rcp_f32_e32 v38, v34
	v_rcp_f32_e32 v39, v35
	v_rcp_f32_e32 v40, v36
	v_rcp_f32_e32 v41, v37
	v_med3_f32 v26, v26, s95, v182
	v_med3_f32 v27, v27, s95, v182
	v_med3_f32 v28, v28, s95, v182
	v_med3_f32 v29, v29, s95, v182
	v_pk_mul_f32 v[28:29], v[28:29], s[56:57] op_sel_hi:[1,0]
	v_pk_mul_f32 v[26:27], v[26:27], s[56:57] op_sel_hi:[1,0]
	v_exp_f32_e32 v28, v28
	v_exp_f32_e32 v26, v26
	v_exp_f32_e32 v27, v27
	v_exp_f32_e32 v29, v29
	s_waitcnt lgkmcnt(1)
	v_lshlrev_b32_e32 v48, 16, v30
	v_and_b32_e32 v49, 0xffff0000, v30
	v_lshlrev_b32_e32 v30, 16, v31
	v_and_b32_e32 v31, 0xffff0000, v31
	s_waitcnt lgkmcnt(0)
	v_lshlrev_b32_e32 v52, 16, v32
	v_and_b32_e32 v53, 0xffff0000, v32
	v_lshlrev_b32_e32 v32, 16, v33
	v_and_b32_e32 v33, 0xffff0000, v33
	v_pk_mul_f32 v[30:31], v[36:37], v[30:31]
	v_pk_mul_f32 v[34:35], v[34:35], v[48:49]
	v_pk_mul_f32 v[32:33], v[40:41], v[32:33]
	v_pk_mul_f32 v[38:39], v[38:39], v[52:53]
	ds_read_b64 v[42:43], v247 offset:4608
	ds_read_b64 v[44:45], v247 offset:9216
	ds_read_b64 v[46:47], v247 offset:13824
	v_cvt_pk_bf16_f32 v34, v34, v35
	v_cvt_pk_bf16_f32 v35, v30, v31
	v_cvt_pk_bf16_f32 v30, v38, v39
	v_cvt_pk_bf16_f32 v31, v32, v33
	v_sub_f32_e32 v25, v25, v17
	v_sub_f32_e32 v24, v24, v16
	v_sub_f32_e32 v23, v23, v15
	v_sub_f32_e32 v22, v22, v14
	ds_read_b64 v[36:37], v247 offset:23040
	ds_read_b64 v[48:49], v247 offset:27648
	ds_read_b64 v[50:51], v247 offset:32256
	ds_write_b64 v247, v[34:35]
	ds_write_b64 v247, v[30:31] offset:18432
	v_rcp_f32_e32 v30, v26
	v_rcp_f32_e32 v31, v27
	v_rcp_f32_e32 v32, v28
	v_rcp_f32_e32 v33, v29
	v_med3_f32 v22, v22, s95, v182
	v_med3_f32 v23, v23, s95, v182
	v_med3_f32 v24, v24, s95, v182
	v_med3_f32 v25, v25, s95, v182
	v_pk_mul_f32 v[24:25], v[24:25], s[56:57] op_sel_hi:[1,0]
	v_pk_mul_f32 v[22:23], v[22:23], s[56:57] op_sel_hi:[1,0]
	s_waitcnt lgkmcnt(7)
	v_lshlrev_b32_e32 v34, 16, v42
	v_and_b32_e32 v35, 0xffff0000, v42
	v_exp_f32_e32 v22, v22
	v_exp_f32_e32 v23, v23
	v_exp_f32_e32 v24, v24
	v_exp_f32_e32 v25, v25
	v_lshlrev_b32_e32 v38, 16, v43
	v_and_b32_e32 v39, 0xffff0000, v43
	v_pk_mul_f32 v[26:27], v[26:27], v[34:35]
	s_waitcnt lgkmcnt(4)
; __device__ __forceinline__ void mixer_hg2(const Args& a, Frame& F, bool ctx_out) {
;     ...
;             const int rlo = H2_ROWLO(c);
;             const bool do_out = ctx_out || c >= NCTX;
;             mx_bf16x8 aq[KS];
;             {
;                 mx_bf16x8 kf[2][KS], vt[4][2];
;                 if (do_out) {
; #pragma unroll
;                     for (int ks = 0; ks < KS; ++ks) { aq[ks] = frag_row(L, QS, nq0, 32 * ks, lane); kf[0][ks] = frag_row(L + IMG, QS, 32 * cg, 32 * ks, lane); kf[1][ks] = frag_row(L + IMG, QS, 32 * cg + 16, 32 * ks, lane); }
;                 }
; #pragma unroll
;                 for (int te = 0; te < 4; ++te) { vt[te][0] = frag_row8(L + O_VT, 16 * te, 0, lane); vt[te][1] = frag_row8(L + O_VT, 16 * te, 32, lane); }
;                 const mx_bf16x8 ak0 = frag_tr(L + IMG, QS, 0, 16 * w, lane), ak1 = frag_tr(L + IMG, QS, 32, 16 * w, lane);
;                 __builtin_amdgcn_sched_barrier(0);
;                 f32x4 pt0 = ZERO4, pt1 = ZERO4;
;                 if (do_out) {
; #pragma unroll
;                     for (int ks = 0; ks < KS; ++ks) { pt0 = MX_MFMA(kf[0][ks], aq[ks], pt0); pt1 = MX_MFMA(kf[1][ks], aq[ks], pt1); }
;                 }
;                 f32x4 uu[4];
; #pragma unroll
;                 for (int te = 0; te < 4; ++te) { const f32x4 z4 = ZERO4; uu[te] = MX_MFMA(ak0, vt[te][0], z4); }
; #pragma unroll
;                 for (int te = 0; te < 4; ++te) uu[te] = MX_MFMA(ak1, vt[te][1], uu[te]);
;                 __builtin_amdgcn_sched_barrier(0);
;                 if (do_out) {
;                     const int m0 = 32 * cg + 4 * g, m1 = m0 + 16, n = nq0 + i;
;                     v2u pw; pw.x = pk2((m0 <= n) ? pt0[0] : 0.f, (m0 + 1 <= n) ? pt0[1] : 0.f); pw.y = pk2((m0 + 2 <= n) ? pt0[2] : 0.f, (m0 + 3 <= n) ? pt0[3] : 0.f);
;                     *(LAS v2u*)(L + O_P + n * PS + m0 * 2) = pw;
;                     pw.x = pk2((m1 <= n) ? pt1[0] : 0.f, (m1 + 1 <= n) ? pt1[1] : 0.f); pw.y = pk2((m1 + 2 <= n) ? pt1[2] : 0.f, (m1 + 3 <= n) ? pt1[3] : 0.f);
;                     *(LAS v2u*)(L + O_P + n * PS + m1 * 2) = pw;
;                 }
; #pragma unroll
;                 for (int te = 0; te < 4; ++te) accS[te] = accS[te] * fe + uu[te] * fu;
;             }
;             mx_bf16x8 st[2][KS], vo[2][2];
;             if (do_out) {
; #pragma unroll
;                 for (int te = 0; te < 2; ++te)
; #pragma unroll
	v_lshlrev_b32_e32 v34, 16, v36
	v_and_b32_e32 v35, 0xffff0000, v36
	v_lshlrev_b32_e32 v36, 16, v37
	v_and_b32_e32 v37, 0xffff0000, v37
	v_sub_f32_e32 v17, v21, v17
	v_sub_f32_e32 v16, v20, v16
	v_sub_f32_e32 v15, v19, v15
	v_sub_f32_e32 v14, v18, v14
	v_pk_mul_f32 v[28:29], v[28:29], v[38:39]
	v_pk_mul_f32 v[32:33], v[32:33], v[36:37]
	v_pk_mul_f32 v[30:31], v[30:31], v[34:35]
	v_med3_f32 v14, v14, s95, v182
	v_med3_f32 v15, v15, s95, v182
	v_med3_f32 v16, v16, s95, v182
	v_med3_f32 v17, v17, s95, v182
	v_cvt_pk_bf16_f32 v26, v26, v27
	v_cvt_pk_bf16_f32 v27, v28, v29
	v_cvt_pk_bf16_f32 v28, v30, v31
	v_cvt_pk_bf16_f32 v29, v32, v33
	v_pk_mul_f32 v[16:17], v[16:17], s[56:57] op_sel_hi:[1,0]
	v_pk_mul_f32 v[14:15], v[14:15], s[56:57] op_sel_hi:[1,0]
	ds_write_b64 v247, v[26:27] offset:4608
	ds_write_b64 v247, v[28:29] offset:23040
	v_rcp_f32_e32 v26, v22
	v_rcp_f32_e32 v27, v23
	v_rcp_f32_e32 v28, v24
	v_rcp_f32_e32 v29, v25
	v_exp_f32_e32 v14, v14
	v_exp_f32_e32 v15, v15
	v_exp_f32_e32 v16, v16
	v_exp_f32_e32 v17, v17
	v_lshlrev_b32_e32 v30, 16, v44
	v_and_b32_e32 v31, 0xffff0000, v44
	v_lshlrev_b32_e32 v32, 16, v45
	v_and_b32_e32 v33, 0xffff0000, v45
	v_pk_mul_f32 v[24:25], v[24:25], v[32:33]
	v_pk_mul_f32 v[22:23], v[22:23], v[30:31]
	s_waitcnt lgkmcnt(5)
	v_lshlrev_b32_e32 v30, 16, v48
	v_and_b32_e32 v31, 0xffff0000, v48
	v_lshlrev_b32_e32 v32, 16, v49
	v_and_b32_e32 v33, 0xffff0000, v49
	v_pk_mul_f32 v[28:29], v[28:29], v[32:33]
	v_pk_mul_f32 v[26:27], v[26:27], v[30:31]
	v_rcp_f32_e32 v18, v14
	v_rcp_f32_e32 v19, v15
	v_rcp_f32_e32 v20, v16
	v_rcp_f32_e32 v21, v17
	v_cvt_pk_bf16_f32 v22, v22, v23
	v_cvt_pk_bf16_f32 v23, v24, v25
	v_cvt_pk_bf16_f32 v24, v26, v27
	v_cvt_pk_bf16_f32 v25, v28, v29
	ds_write_b64 v247, v[22:23] offset:9216
	ds_write_b64 v247, v[24:25] offset:27648
	v_lshlrev_b32_e32 v22, 16, v46
	v_and_b32_e32 v23, 0xffff0000, v46
	v_lshlrev_b32_e32 v24, 16, v47
	v_and_b32_e32 v25, 0xffff0000, v47
	v_pk_mul_f32 v[16:17], v[16:17], v[24:25]
	v_pk_mul_f32 v[14:15], v[14:15], v[22:23]
	s_waitcnt lgkmcnt(6)
	v_lshlrev_b32_e32 v22, 16, v50
	v_and_b32_e32 v23, 0xffff0000, v50
	v_lshlrev_b32_e32 v24, 16, v51
	v_and_b32_e32 v25, 0xffff0000, v51
	v_pk_mul_f32 v[20:21], v[20:21], v[24:25]
	v_pk_mul_f32 v[18:19], v[18:19], v[22:23]
	v_cvt_pk_bf16_f32 v14, v14, v15
	v_cvt_pk_bf16_f32 v15, v16, v17
	v_cvt_pk_bf16_f32 v16, v18, v19
	v_cvt_pk_bf16_f32 v17, v20, v21
	ds_write_b64 v247, v[14:15] offset:13824
	ds_write_b64 v247, v[16:17] offset:32256
	s_waitcnt lgkmcnt(0)
	s_barrier
	v_add_u32_e32 v42, v230, v232
	ds_read_b128 v[14:17], v42
	ds_read_b128 v[18:21], v42 offset:64
	ds_read_b128 v[30:33], v54 offset:18432
	ds_read_b128 v[38:41], v54 offset:18496
	ds_read_b128 v[26:29], v54 offset:23040
	ds_read_b128 v[34:37], v54 offset:23104
	ds_read_b128 v[22:25], v42 offset:128
	ds_read_b128 v[42:45], v42 offset:192
	ds_read_b128 v[50:53], v54 offset:18560
	ds_read_b128 v[58:61], v54 offset:18624
	ds_read_b128 v[46:49], v54 offset:23168
	ds_read_b128 v[54:57], v54 offset:23232
	s_waitcnt lgkmcnt(9)
	v_mfma_f32_16x16x32_bf16 v[62:65], v[30:33], v[14:17], v[2:5]
	s_waitcnt lgkmcnt(7)
	v_mfma_f32_16x16x32_bf16 v[66:69], v[26:29], v[14:17], v[2:5]
	v_mfma_f32_16x16x32_bf16 v[62:65], v[38:41], v[18:21], v[62:65]
	s_waitcnt lgkmcnt(6)
	v_mfma_f32_16x16x32_bf16 v[66:69], v[34:37], v[18:21], v[66:69]
	s_waitcnt lgkmcnt(3)
	v_mfma_f32_16x16x32_bf16 v[62:65], v[50:53], v[22:25], v[62:65]
	s_waitcnt lgkmcnt(1)
	v_mfma_f32_16x16x32_bf16 v[66:69], v[46:49], v[22:25], v[66:69]
	v_mfma_f32_16x16x32_bf16 v[62:65], v[58:61], v[42:45], v[62:65]
	s_waitcnt lgkmcnt(0)
	v_mfma_f32_16x16x32_bf16 v[66:69], v[54:57], v[42:45], v[66:69]
	s_nop 5
	v_cndmask_b32_e64 v62, v62, 0, s[8:9]
	v_cndmask_b32_e64 v63, 0, v63, s[10:11]
	v_cvt_pk_bf16_f32 v62, v62, v63
	v_cndmask_b32_e64 v63, v64, 0, s[12:13]
	v_cndmask_b32_e64 v64, v65, 0, s[14:15]
	v_cvt_pk_bf16_f32 v63, v63, v64
	v_add_u32_e32 v64, v233, v234
	ds_write_b64 v64, v[62:63]
	v_cndmask_b32_e64 v62, v66, 0, s[16:17]
	v_cndmask_b32_e64 v63, v67, 0, s[18:19]
	v_cvt_pk_bf16_f32 v62, v62, v63
	v_cndmask_b32_e64 v63, v68, 0, s[20:21]
	v_cndmask_b32_e64 v64, v69, 0, s[22:23]
	v_cvt_pk_bf16_f32 v63, v63, v64
	v_add_u32_e32 v64, v233, v235
	ds_write_b64 v64, v[62:63]
	v_add_u32_e32 v90, v242, v232
	ds_read_b128 v[62:65], v90
	ds_read_b128 v[66:69], v90 offset:64
	ds_read_b128 v[70:73], v90 offset:128
	ds_read_b128 v[74:77], v90 offset:192
	ds_read_b128 v[78:81], v90 offset:4608
	ds_read_b128 v[82:85], v90 offset:4672
	ds_read_b128 v[86:89], v90 offset:4736
	ds_read_b128 v[90:93], v90 offset:4800
	s_waitcnt lgkmcnt(0)
	s_barrier
	v_add_u32_e32 v98, v233, v232
	v_add_u32_e32 v114, v243, v232
	ds_read_b128 v[94:97], v98
	ds_read_b128 v[98:101], v98 offset:64
	ds_read_b128 v[102:105], v114 offset:55296
	ds_read_b128 v[106:109], v114 offset:55360
	ds_read_b128 v[110:113], v114 offset:57856
	ds_read_b128 v[114:117], v114 offset:57920
	s_waitcnt lgkmcnt(3)
	v_mfma_f32_16x16x32_bf16 v[102:105], v[102:105], v[94:97], v[2:5]
	s_add_i32 s6, s6, s3
	s_cmpk_gt_i32 s6, 0xff
	s_waitcnt lgkmcnt(1)
	v_mfma_f32_16x16x32_bf16 v[94:97], v[110:113], v[94:97], v[2:5]
	v_add_u32_e32 v110, s7, v248
	v_ashrrev_i32_e32 v111, 31, v110
	v_lshlrev_b64 v[110:111], 12, v[110:111]
	v_mfma_f32_16x16x32_bf16 v[102:105], v[62:65], v[14:17], v[102:105]
	v_mfma_f32_16x16x32_bf16 v[94:97], v[78:81], v[14:17], v[94:97]
	v_mfma_f32_16x16x32_bf16 v[102:105], v[66:69], v[18:21], v[102:105]
	v_mfma_f32_16x16x32_bf16 v[94:97], v[82:85], v[18:21], v[94:97]
	v_mfma_f32_16x16x32_bf16 v[102:105], v[70:73], v[22:25], v[102:105]
	v_mfma_f32_16x16x32_bf16 v[94:97], v[86:89], v[22:25], v[94:97]
	v_mfma_f32_16x16x32_bf16 v[102:105], v[74:77], v[42:45], v[102:105]
	v_mfma_f32_16x16x32_bf16 v[94:97], v[90:93], v[42:45], v[94:97]
	v_mfma_f32_16x16x32_bf16 v[102:105], v[106:109], v[98:101], v[102:105]
	v_lshl_add_u64 v[106:107], v[194:195], 0, v[110:111]
	s_waitcnt lgkmcnt(0)
	v_mfma_f32_16x16x32_bf16 v[94:97], v[114:117], v[98:101], v[94:97]
	s_nop 4
	v_cvt_pk_bf16_f32 v102, v102, v103
	v_cvt_pk_bf16_f32 v103, v104, v105
	s_nop 0
	v_cvt_pk_bf16_f32 v94, v94, v95
	v_cvt_pk_bf16_f32 v95, v96, v97
	global_store_dwordx2 v[106:107], v[102:103], off
	global_store_dwordx2 v[106:107], v[94:95], off offset:32
	s_waitcnt lgkmcnt(0)
	s_barrier
	s_cbranch_scc1 .LBB0_524

; #define LAS __attribute__((address_space(3)))
; __device__ __forceinline__ void mixer_hg2(const Args& a, Frame& F, bool ctx_out) {
;     ...
;             H2_STAGE(u);
;             MX_BAR();
;             { const int cn = (c + PF < NCH) ? c + PF : NCH - 1; H2_LOAD(cn, u); }
;             f32x4 fe, fu;
;             {
;                 unsigned one2_ = 0x3F803F80u; asm volatile("" : "+v"(one2_));
;                 typedef unsigned u4_ __attribute__((ext_vector_type(4)));
;                 const mx_bf16x8 ones = __builtin_bit_cast(mx_bf16x8, (u4_){one2_, one2_, one2_, one2_});
;                 const mx_bf16x8 a0 = frag_tr(L + 2 * IMG, QS, 0, 16 * w, lane), a1 = frag_tr(L + 2 * IMG, QS, 32, 16 * w, lane);
;                 const f32x4 z = ZERO4;
;                 f32x4 ct[4];
;                 ct[0] = MX_MFMA(a0, bt0, z); ct[1] = MX_MFMA(a0, bt1, z);
;                 const f32x4 cref = MX_MFMA(a0, ones, z);
;                 ct[2] = MX_MFMA(a1, bt0, cref); ct[3] = MX_MFMA(a1, bt1, cref);
;                 const f32x4 cend = MX_MFMA(a1, ones, cref);
;                 fe = (f32x4){__expf(cend[0]), __expf(cend[1]), __expf(cend[2]), __expf(cend[3])};
;                 fu = (f32x4){__expf(cend[0] - cref[0]), __expf(cend[1] - cref[1]), __expf(cend[2] - cref[2]), __expf(cend[3] - cref[3])};
;                 const f32x4 fs = {__expf(cref[0]), __expf(cref[1]), __expf(cref[2]), __expf(cref[3])};
; #pragma unroll
;                 for (int te = 0; te < 4; ++te) { const f32x4 s = accS[te] * fs; v2u sw; sw.x = pk2(s[0], s[1]); sw.y = pk2(s[2], s[3]);
;                     *(LAS v2u*)(L + O_ST + (16 * te + i) * QS + (16 * w + 4 * g) * 2) = sw; }
; #pragma unroll
;                 for (int t = 0; t < 4; ++t) {
;                     LAS unsigned char* pq = L + (16 * t + i) * QS + (16 * w + 4 * g) * 2;
;                     const v2u qw = *(const LAS v2u*)pq, kw = *(const LAS v2u*)(pq + IMG);
;                     const f32x4 dd = ct[t] - cref;
;                     const f32x4 tt = (f32x4){__builtin_amdgcn_fmed3f(dd[0], -80.f, 80.f), __builtin_amdgcn_fmed3f(dd[1], -80.f, 80.f), __builtin_amdgcn_fmed3f(dd[2], -80.f, 80.f), __builtin_amdgcn_fmed3f(dd[3], -80.f, 80.f)} * 1.4426950408889634f;
;                     const f32x4 e1 = {__builtin_amdgcn_exp2f(tt[0]), __builtin_amdgcn_exp2f(tt[1]), __builtin_amdgcn_exp2f(tt[2]), __builtin_amdgcn_exp2f(tt[3])};
.LBB0_512:
	s_add_i32 s29, s31, 1
	s_add_i32 s36, s30, -1
	v_sub_co_u32_e64 v122, s[34:35], s31, 3
	s_and_b64 s[26:27], s[24:25], exec
	v_readfirstlane_b32 s26, v122
	s_cselect_b32 s26, s26, s36
	s_lshl_b32 s37, s26, 6
	s_add_i32 s40, s30, 0xffffffbf
	s_and_b64 s[26:27], s[24:25], exec
	s_cselect_b32 s26, s29, s40
	s_lshl_b32 s26, s26, 6
	s_add_i32 s40, s26, s33
	s_cmp_gt_u32 s31, 3
	s_cselect_b64 s[26:27], -1, 0
	s_add_i32 s37, s37, s7
	s_and_b64 s[34:35], s[34:35], exec
	s_cselect_b32 s34, s40, s37
	s_waitcnt vmcnt(4)
	ds_write_b128 v251, v[94:97]
	s_waitcnt vmcnt(3)
	ds_write_b128 v251, v[98:101] offset:18432
	ds_write_b128 v251, v[102:105] offset:36864
	ds_write_b128 v250, v[110:113]
	s_waitcnt vmcnt(2)
	ds_write_b128 v250, v[106:109] offset:18432
	s_waitcnt vmcnt(1)
	ds_write_b128 v250, v[114:117] offset:36864
	s_waitcnt vmcnt(0)
	ds_write_b16 v249, v118 offset:55296
	ds_write_b16_d16_hi v249, v118 offset:55456
	ds_write_b16 v249, v119 offset:55616
	ds_write_b16_d16_hi v249, v119 offset:55776
	ds_write_b16 v249, v120 offset:55936
	ds_write_b16_d16_hi v249, v120 offset:56096
	ds_write_b16 v249, v121 offset:56256
	ds_write_b16_d16_hi v249, v121 offset:56416
	v_add_u32_e32 v94, s34, v237
	v_add_u32_e32 v106, s34, v238
	v_ashrrev_i32_e32 v95, 31, v94
	v_ashrrev_i32_e32 v107, 31, v106
	v_lshlrev_b64 v[94:95], 11, v[94:95]
	v_lshlrev_b64 v[106:107], 11, v[106:107]
	v_lshl_add_u64 v[94:95], v[94:95], 0, v[200:201]
	v_lshl_add_u64 v[106:107], v[106:107], 0, v[200:201]
	v_or_b32_e32 v118, s34, v185
	v_lshlrev_b64 v[102:103], 1, v[94:95]
	v_lshlrev_b64 v[114:115], 1, v[106:107]
	v_ashrrev_i32_e32 v119, 31, v118
	s_waitcnt lgkmcnt(0)
	s_barrier
	v_lshl_add_u64 v[94:95], v[188:189], 0, v[102:103]
	v_lshl_add_u64 v[98:99], v[196:197], 0, v[102:103]
	v_lshl_add_u64 v[102:103], v[198:199], 0, v[102:103]
	v_lshl_add_u64 v[106:107], v[188:189], 0, v[114:115]
	v_lshlrev_b64 v[118:119], 12, v[118:119]
	global_load_dwordx4 v[102:105], v[102:103], off
	v_lshl_add_u64 v[118:119], v[216:217], 0, v[118:119]
	global_load_dwordx4 v[110:113], v[106:107], off
	v_lshl_add_u64 v[106:107], v[196:197], 0, v[114:115]
	v_lshl_add_u64 v[114:115], v[198:199], 0, v[114:115]
	global_load_dwordx4 v[94:97], v[94:95], off
	v_mov_b32_e32 v126, 0x3f803f80
	global_load_dwordx4 v[98:101], v[98:99], off
	s_or_b64 s[34:35], s[4:5], s[26:27]
	global_load_dwordx4 v[106:109], v[106:107], off
	s_and_b64 vcc, exec, s[34:35]
	global_load_dwordx4 v[114:117], v[114:115], off
	s_nop 0
	global_load_dwordx4 v[118:121], v[118:119], off
	ds_read_b64_tr_b16 v[122:123], v245 offset:36864
	ds_read_b64_tr_b16 v[124:125], v245 offset:38016
	ds_read_b64_tr_b16 v[138:139], v245 offset:46080
	ds_read_b64_tr_b16 v[140:141], v245 offset:47232
	v_mov_b32_e32 v127, v126
	v_mov_b32_e32 v128, v126
	v_mov_b32_e32 v129, v126
	s_waitcnt lgkmcnt(2)
	v_mfma_f32_16x16x32_bf16 v[142:145], v[122:125], v[10:13], v[2:5]
	v_mfma_f32_16x16x32_bf16 v[146:149], v[122:125], v[6:9], v[2:5]
	v_mfma_f32_16x16x32_bf16 v[122:125], v[122:125], v[126:129], v[2:5]
	s_waitcnt lgkmcnt(0)
	v_mfma_f32_16x16x32_bf16 v[134:137], v[138:141], v[10:13], v[122:125]
	v_mfma_f32_16x16x32_bf16 v[130:133], v[138:141], v[6:9], v[122:125]
	s_nop 4
	v_sub_f32_e32 v145, v145, v125
	v_sub_f32_e32 v144, v144, v124
	v_sub_f32_e32 v143, v143, v123
	v_mfma_f32_16x16x32_bf16 v[126:129], v[138:141], v[126:129], v[122:125]
	v_mul_f32_e32 v138, 0x3fb8aa3b, v122
	v_mul_f32_e32 v139, 0x3fb8aa3b, v123
	v_mul_f32_e32 v140, 0x3fb8aa3b, v124
	v_mul_f32_e32 v141, 0x3fb8aa3b, v125
	v_exp_f32_e32 v138, v138
	v_exp_f32_e32 v139, v139
	v_exp_f32_e32 v140, v140
	v_exp_f32_e32 v141, v141
	v_sub_f32_e32 v142, v142, v122
	v_pk_mul_f32 v[152:153], v[214:215], v[138:139]
	v_med3_f32 v142, v142, s95, v182
	v_pk_mul_f32 v[150:151], v[218:219], v[140:141]
	v_cvt_pk_bf16_f32 v152, v152, v153
	v_cvt_pk_bf16_f32 v153, v150, v151
	ds_write_b64 v246, v[152:153]
	v_pk_mul_f32 v[150:151], v[212:213], v[140:141]
	v_pk_mul_f32 v[152:153], v[210:211], v[138:139]
	v_med3_f32 v143, v143, s95, v182
	v_cvt_pk_bf16_f32 v152, v152, v153
	v_cvt_pk_bf16_f32 v153, v150, v151
	v_med3_f32 v144, v144, s95, v182
	v_med3_f32 v145, v145, s95, v182
	ds_write_b64 v246, v[152:153] offset:4608
	v_pk_mul_f32 v[150:151], v[208:209], v[140:141]
	v_pk_mul_f32 v[152:153], v[206:207], v[138:139]
	v_pk_mul_f32 v[140:141], v[204:205], v[140:141]
	v_pk_mul_f32 v[138:139], v[202:203], v[138:139]
	v_pk_mul_f32 v[144:145], v[144:145], s[56:57] op_sel_hi:[1,0]
	v_pk_mul_f32 v[142:143], v[142:143], s[56:57] op_sel_hi:[1,0]
	v_cvt_pk_bf16_f32 v152, v152, v153
	v_cvt_pk_bf16_f32 v153, v150, v151
	v_cvt_pk_bf16_f32 v138, v138, v139
	v_cvt_pk_bf16_f32 v139, v140, v141
	v_exp_f32_e32 v142, v142
	v_exp_f32_e32 v143, v143
	v_exp_f32_e32 v144, v144
	v_exp_f32_e32 v145, v145
	ds_write_b64 v246, v[152:153] offset:9216
	ds_write_b64 v246, v[138:139] offset:13824
	ds_read_b64 v[138:139], v247
	ds_read_b64 v[140:141], v247 offset:18432
	v_rcp_f32_e32 v150, v142
	v_rcp_f32_e32 v151, v143
	v_rcp_f32_e32 v152, v144
	v_rcp_f32_e32 v153, v145
	s_waitcnt lgkmcnt(1)
	v_lshlrev_b32_e32 v154, 16, v138
	v_and_b32_e32 v155, 0xffff0000, v138
	v_lshlrev_b32_e32 v138, 16, v139
	v_and_b32_e32 v139, 0xffff0000, v139
	v_pk_mul_f32 v[138:139], v[144:145], v[138:139]
	v_pk_mul_f32 v[142:143], v[142:143], v[154:155]
	s_waitcnt lgkmcnt(0)
; #define LAS __attribute__((address_space(3)))
; __device__ __forceinline__ unsigned pk2(float lo, float hi) { const f32x2_t v = {lo, hi}; const bf16x2_t b = __builtin_convertvector(v, bf16x2_t); return __builtin_bit_cast(unsigned, b); }
; #define MX_BAR() do { asm volatile("s_waitcnt lgkmcnt(0)" ::: "memory"); __builtin_amdgcn_s_barrier(); if (MXP_BAR > 1) __builtin_amdgcn_s_barrier(); asm volatile("" ::: "memory"); } while (0)
; __device__ __forceinline__ void mixer_hg2(const Args& a, Frame& F, bool ctx_out) {
;     ...
; #pragma unroll
;                 for (int t = 0; t < 4; ++t) {
;                     LAS unsigned char* pq = L + (16 * t + i) * QS + (16 * w + 4 * g) * 2;
;                     const v2u qw = *(const LAS v2u*)pq, kw = *(const LAS v2u*)(pq + IMG);
;                     const f32x4 dd = ct[t] - cref;
;                     const f32x4 tt = (f32x4){__builtin_amdgcn_fmed3f(dd[0], -80.f, 80.f), __builtin_amdgcn_fmed3f(dd[1], -80.f, 80.f), __builtin_amdgcn_fmed3f(dd[2], -80.f, 80.f), __builtin_amdgcn_fmed3f(dd[3], -80.f, 80.f)} * 1.4426950408889634f;
;                     const f32x4 e1 = {__builtin_amdgcn_exp2f(tt[0]), __builtin_amdgcn_exp2f(tt[1]), __builtin_amdgcn_exp2f(tt[2]), __builtin_amdgcn_exp2f(tt[3])};
;                     const f32x4 e2 = {__builtin_amdgcn_rcpf(e1[0]), __builtin_amdgcn_rcpf(e1[1]), __builtin_amdgcn_rcpf(e1[2]), __builtin_amdgcn_rcpf(e1[3])};
;                     const f32x4 q4 = (f32x4){bflo(qw.x), bfhi(qw.x), bflo(qw.y), bfhi(qw.y)} * e1, k4 = (f32x4){bflo(kw.x), bfhi(kw.x), bflo(kw.y), bfhi(kw.y)} * e2;
;                     v2u qo, ko;
;                     qo.x = pk2(q4[0], q4[1]); qo.y = pk2(q4[2], q4[3]);
;                     ko.x = pk2(k4[0], k4[1]); ko.y = pk2(k4[2], k4[3]);
;                     *(LAS v2u*)pq = qo; *(LAS v2u*)(pq + IMG) = ko;
;                 }
;             }
;             MX_BAR();
;             const int rlo = H2_ROWLO(c);
;             const bool do_out = ctx_out || c >= NCTX;
;             mx_bf16x8 aq[KS];
;             {
;                 mx_bf16x8 kf[2][KS], vt[4][2];
;                 if (do_out) {
; #pragma unroll
;                     for (int ks = 0; ks < KS; ++ks) { aq[ks] = frag_row(L, QS, nq0, 32 * ks, lane); kf[0][ks] = frag_row(L + IMG, QS, 32 * cg, 32 * ks, lane); kf[1][ks] = frag_row(L + IMG, QS, 32 * cg + 16, 32 * ks, lane); }
;                 }
	v_lshlrev_b32_e32 v144, 16, v140
	v_and_b32_e32 v145, 0xffff0000, v140
	v_lshlrev_b32_e32 v140, 16, v141
	v_and_b32_e32 v141, 0xffff0000, v141
	v_pk_mul_f32 v[140:141], v[152:153], v[140:141]
	v_pk_mul_f32 v[144:145], v[150:151], v[144:145]
	v_cvt_pk_bf16_f32 v142, v142, v143
	v_cvt_pk_bf16_f32 v143, v138, v139
	v_cvt_pk_bf16_f32 v138, v144, v145
	v_cvt_pk_bf16_f32 v139, v140, v141
	ds_write_b64 v247, v[142:143]
	ds_write_b64 v247, v[138:139] offset:18432
	v_sub_f32_e32 v145, v149, v125
	v_sub_f32_e32 v144, v148, v124
	v_sub_f32_e32 v143, v147, v123
	v_sub_f32_e32 v142, v146, v122
	v_med3_f32 v142, v142, s95, v182
	v_med3_f32 v143, v143, s95, v182
	v_med3_f32 v144, v144, s95, v182
	v_med3_f32 v145, v145, s95, v182
	v_pk_mul_f32 v[144:145], v[144:145], s[56:57] op_sel_hi:[1,0]
	v_pk_mul_f32 v[142:143], v[142:143], s[56:57] op_sel_hi:[1,0]
	v_exp_f32_e32 v144, v144
	v_exp_f32_e32 v142, v142
	v_exp_f32_e32 v143, v143
	v_exp_f32_e32 v145, v145
	ds_read_b64 v[138:139], v247 offset:4608
	ds_read_b64 v[140:141], v247 offset:23040
	v_rcp_f32_e32 v146, v142
	v_rcp_f32_e32 v147, v143
	v_rcp_f32_e32 v148, v144
	v_rcp_f32_e32 v149, v145
	v_sub_f32_e32 v137, v137, v125
	v_sub_f32_e32 v136, v136, v124
	v_sub_f32_e32 v135, v135, v123
	v_sub_f32_e32 v134, v134, v122
	s_waitcnt lgkmcnt(1)
	v_lshlrev_b32_e32 v150, 16, v138
	v_and_b32_e32 v151, 0xffff0000, v138
	v_lshlrev_b32_e32 v138, 16, v139
	v_and_b32_e32 v139, 0xffff0000, v139
	v_med3_f32 v134, v134, s95, v182
	v_med3_f32 v135, v135, s95, v182
	v_med3_f32 v136, v136, s95, v182
	v_med3_f32 v137, v137, s95, v182
	v_pk_mul_f32 v[138:139], v[144:145], v[138:139]
	v_pk_mul_f32 v[142:143], v[142:143], v[150:151]
	s_waitcnt lgkmcnt(0)
	v_lshlrev_b32_e32 v144, 16, v140
	v_and_b32_e32 v145, 0xffff0000, v140
	v_lshlrev_b32_e32 v140, 16, v141
	v_and_b32_e32 v141, 0xffff0000, v141
	v_pk_mul_f32 v[136:137], v[136:137], s[56:57] op_sel_hi:[1,0]
	v_pk_mul_f32 v[134:135], v[134:135], s[56:57] op_sel_hi:[1,0]
	v_pk_mul_f32 v[140:141], v[148:149], v[140:141]
	v_pk_mul_f32 v[144:145], v[146:147], v[144:145]
	v_cvt_pk_bf16_f32 v142, v142, v143
	v_cvt_pk_bf16_f32 v143, v138, v139
	v_exp_f32_e32 v134, v134
	v_exp_f32_e32 v135, v135
	v_exp_f32_e32 v136, v136
	v_exp_f32_e32 v137, v137
	v_cvt_pk_bf16_f32 v138, v144, v145
	v_cvt_pk_bf16_f32 v139, v140, v141
	ds_write_b64 v247, v[142:143] offset:4608
	ds_write_b64 v247, v[138:139] offset:23040
	ds_read_b64 v[138:139], v247 offset:9216
	ds_read_b64 v[140:141], v247 offset:27648
	v_rcp_f32_e32 v142, v134
	v_rcp_f32_e32 v143, v135
	v_rcp_f32_e32 v144, v136
	v_rcp_f32_e32 v145, v137
	v_sub_f32_e32 v133, v133, v125
	v_sub_f32_e32 v132, v132, v124
	v_sub_f32_e32 v131, v131, v123
	v_sub_f32_e32 v130, v130, v122
	s_waitcnt lgkmcnt(1)
	v_lshlrev_b32_e32 v146, 16, v138
	v_and_b32_e32 v147, 0xffff0000, v138
	v_lshlrev_b32_e32 v138, 16, v139
	v_and_b32_e32 v139, 0xffff0000, v139
	v_med3_f32 v130, v130, s95, v182
	v_med3_f32 v131, v131, s95, v182
	v_med3_f32 v132, v132, s95, v182
	v_med3_f32 v133, v133, s95, v182
	v_pk_mul_f32 v[136:137], v[136:137], v[138:139]
	v_pk_mul_f32 v[134:135], v[134:135], v[146:147]
	s_waitcnt lgkmcnt(0)
	v_lshlrev_b32_e32 v138, 16, v140
	v_and_b32_e32 v139, 0xffff0000, v140
	v_lshlrev_b32_e32 v140, 16, v141
	v_and_b32_e32 v141, 0xffff0000, v141
	v_pk_mul_f32 v[132:133], v[132:133], s[56:57] op_sel_hi:[1,0]
	v_pk_mul_f32 v[130:131], v[130:131], s[56:57] op_sel_hi:[1,0]
	v_pk_mul_f32 v[140:141], v[144:145], v[140:141]
	v_pk_mul_f32 v[138:139], v[142:143], v[138:139]
	v_cvt_pk_bf16_f32 v134, v134, v135
	v_cvt_pk_bf16_f32 v135, v136, v137
	v_exp_f32_e32 v130, v130
	v_exp_f32_e32 v131, v131
	v_exp_f32_e32 v132, v132
	v_exp_f32_e32 v133, v133
	v_cvt_pk_bf16_f32 v136, v138, v139
	v_cvt_pk_bf16_f32 v137, v140, v141
	ds_write_b64 v247, v[134:135] offset:9216
	ds_write_b64 v247, v[136:137] offset:27648
	ds_read_b64 v[134:135], v247 offset:13824
	ds_read_b64 v[136:137], v247 offset:32256
	v_rcp_f32_e32 v138, v130
	v_rcp_f32_e32 v139, v131
	v_rcp_f32_e32 v140, v132
	v_rcp_f32_e32 v141, v133
	s_waitcnt lgkmcnt(1)
	v_lshlrev_b32_e32 v142, 16, v134
	v_and_b32_e32 v143, 0xffff0000, v134
	v_lshlrev_b32_e32 v134, 16, v135
	v_and_b32_e32 v135, 0xffff0000, v135
	v_pk_mul_f32 v[132:133], v[132:133], v[134:135]
	v_pk_mul_f32 v[130:131], v[130:131], v[142:143]
	s_waitcnt lgkmcnt(0)
	v_lshlrev_b32_e32 v134, 16, v136
	v_and_b32_e32 v135, 0xffff0000, v136
	v_lshlrev_b32_e32 v136, 16, v137
	v_and_b32_e32 v137, 0xffff0000, v137
	v_pk_mul_f32 v[136:137], v[140:141], v[136:137]
	v_pk_mul_f32 v[134:135], v[138:139], v[134:135]
	v_cvt_pk_bf16_f32 v130, v130, v131
	v_cvt_pk_bf16_f32 v131, v132, v133
	v_cvt_pk_bf16_f32 v132, v134, v135
	v_cvt_pk_bf16_f32 v133, v136, v137
	ds_write_b64 v247, v[130:131] offset:13824
	ds_write_b64 v247, v[132:133] offset:32256
	s_waitcnt lgkmcnt(0)
	s_barrier
	s_cbranch_vccz .LBB0_514
	v_add_u32_e32 v42, v230, v232
	v_add_u32_e32 v54, v231, v232
	ds_read_b128 v[14:17], v42
	ds_read_b128 v[18:21], v42 offset:64
	ds_read_b128 v[30:33], v54 offset:18432
	ds_read_b128 v[38:41], v54 offset:18496
	ds_read_b128 v[26:29], v54 offset:23040
	ds_read_b128 v[34:37], v54 offset:23104
	ds_read_b128 v[22:25], v42 offset:128
	ds_read_b128 v[42:45], v42 offset:192
	ds_read_b128 v[50:53], v54 offset:18560
	ds_read_b128 v[58:61], v54 offset:18624
	ds_read_b128 v[46:49], v54 offset:23168
	ds_read_b128 v[54:57], v54 offset:23232
; #define LAS __attribute__((address_space(3)))
; __device__ __forceinline__ unsigned pk2(float lo, float hi) { const f32x2_t v = {lo, hi}; const bf16x2_t b = __builtin_convertvector(v, bf16x2_t); return __builtin_bit_cast(unsigned, b); }
; #define MX_MFMA(a, b, c) __builtin_amdgcn_mfma_f32_16x16x32_bf16((a), (b), (c), 0, 0, 0)
; __device__ __forceinline__ void mixer_hg2(const Args& a, Frame& F, bool ctx_out) {
;     ...
; #pragma unroll
;                 for (int te = 0; te < 4; ++te) { vt[te][0] = frag_row8(L + O_VT, 16 * te, 0, lane); vt[te][1] = frag_row8(L + O_VT, 16 * te, 32, lane); }
;                 const mx_bf16x8 ak0 = frag_tr(L + IMG, QS, 0, 16 * w, lane), ak1 = frag_tr(L + IMG, QS, 32, 16 * w, lane);
;                 __builtin_amdgcn_sched_barrier(0);
;                 f32x4 pt0 = ZERO4, pt1 = ZERO4;
;                 if (do_out) {
; #pragma unroll
;                     for (int ks = 0; ks < KS; ++ks) { pt0 = MX_MFMA(kf[0][ks], aq[ks], pt0); pt1 = MX_MFMA(kf[1][ks], aq[ks], pt1); }
;                 }
;                 f32x4 uu[4];
; #pragma unroll
;                 for (int te = 0; te < 4; ++te) { const f32x4 z4 = ZERO4; uu[te] = MX_MFMA(ak0, vt[te][0], z4); }
; #pragma unroll
;                 for (int te = 0; te < 4; ++te) uu[te] = MX_MFMA(ak1, vt[te][1], uu[te]);
;                 __builtin_amdgcn_sched_barrier(0);
;                 if (do_out) {
;                     const int m0 = 32 * cg + 4 * g, m1 = m0 + 16, n = nq0 + i;
;                     v2u pw; pw.x = pk2((m0 <= n) ? pt0[0] : 0.f, (m0 + 1 <= n) ? pt0[1] : 0.f); pw.y = pk2((m0 + 2 <= n) ? pt0[2] : 0.f, (m0 + 3 <= n) ? pt0[3] : 0.f);
;                     *(LAS v2u*)(L + O_P + n * PS + m0 * 2) = pw;
;                     pw.x = pk2((m1 <= n) ? pt1[0] : 0.f, (m1 + 1 <= n) ? pt1[1] : 0.f); pw.y = pk2((m1 + 2 <= n) ? pt1[2] : 0.f, (m1 + 3 <= n) ? pt1[3] : 0.f);
;                     *(LAS v2u*)(L + O_P + n * PS + m1 * 2) = pw;
;                 }
.LBB0_514:
	ds_read_b128 v[138:141], v244 offset:55296
	ds_read_b128 v[130:133], v244 offset:55360
	ds_read_b128 v[142:145], v244 offset:57856
	ds_read_b128 v[134:137], v244 offset:57920
	ds_read_b128 v[158:161], v244 offset:60416
	ds_read_b128 v[146:149], v244 offset:60480
	ds_read_b128 v[162:165], v244 offset:62976
	ds_read_b128 v[150:153], v244 offset:63040
	ds_read_b64_tr_b16 v[170:171], v245 offset:18432
	ds_read_b64_tr_b16 v[172:173], v245 offset:19584
	ds_read_b64_tr_b16 v[166:167], v245 offset:27648
	ds_read_b64_tr_b16 v[168:169], v245 offset:28800
	v_cndmask_b32_e64 v154, 0, 1, s[34:35]
	v_cmp_ne_u32_e64 s[26:27], 1, v154
	s_andn2_b64 vcc, exec, s[34:35]
	v_mov_b32_e32 v174, v2
	v_mov_b32_e32 v175, v2
	v_mov_b32_e32 v176, v2
	v_mov_b32_e32 v177, v2
	v_mov_b32_e32 v154, v2
	v_mov_b32_e32 v155, v2
	v_mov_b32_e32 v156, v2
	v_mov_b32_e32 v157, v2
	s_cbranch_vccnz .LBB0_516
	s_waitcnt lgkmcnt(14)
	v_mfma_f32_16x16x32_bf16 v[154:157], v[30:33], v[14:17], v[2:5]
	v_mfma_f32_16x16x32_bf16 v[174:177], v[26:29], v[14:17], v[2:5]
	v_mfma_f32_16x16x32_bf16 v[154:157], v[38:41], v[18:21], v[154:157]
	v_mfma_f32_16x16x32_bf16 v[174:177], v[34:37], v[18:21], v[174:177]
	v_mfma_f32_16x16x32_bf16 v[154:157], v[50:53], v[22:25], v[154:157]
	s_waitcnt lgkmcnt(13)
	v_mfma_f32_16x16x32_bf16 v[178:181], v[46:49], v[22:25], v[174:177]
	v_mfma_f32_16x16x32_bf16 v[174:177], v[58:61], v[42:45], v[154:157]
	s_waitcnt lgkmcnt(12)
	v_mfma_f32_16x16x32_bf16 v[154:157], v[54:57], v[42:45], v[178:181]
.LBB0_516:
	s_waitcnt lgkmcnt(2)
	v_mfma_f32_16x16x32_bf16 v[138:141], v[170:173], v[138:141], v[2:5]
	v_mfma_f32_16x16x32_bf16 v[178:181], v[170:173], v[142:145], v[2:5]
	v_mfma_f32_16x16x32_bf16 v[158:161], v[170:173], v[158:161], v[2:5]
	v_mfma_f32_16x16x32_bf16 v[162:165], v[170:173], v[162:165], v[2:5]
	s_waitcnt lgkmcnt(0)
	v_mfma_f32_16x16x32_bf16 v[142:145], v[166:169], v[130:133], v[138:141]
	v_mfma_f32_16x16x32_bf16 v[138:141], v[166:169], v[134:137], v[178:181]
	v_mfma_f32_16x16x32_bf16 v[134:137], v[166:169], v[146:149], v[158:161]
	v_mfma_f32_16x16x32_bf16 v[130:133], v[166:169], v[150:153], v[162:165]
	s_and_b64 vcc, exec, s[26:27]
	s_cbranch_vccnz .LBB0_518
	v_cndmask_b32_e64 v146, v174, 0, s[8:9]
	v_cndmask_b32_e64 v147, 0, v175, s[10:11]
	v_cvt_pk_bf16_f32 v146, v146, v147
	v_cndmask_b32_e64 v147, v176, 0, s[12:13]
	v_cndmask_b32_e64 v148, v177, 0, s[14:15]
	v_cvt_pk_bf16_f32 v147, v147, v148
	v_add_u32_e32 v148, v233, v234
	ds_write_b64 v148, v[146:147]
	v_cndmask_b32_e64 v146, v154, 0, s[16:17]
	v_cndmask_b32_e64 v147, v155, 0, s[18:19]
	v_cvt_pk_bf16_f32 v146, v146, v147
	v_cndmask_b32_e64 v147, v156, 0, s[20:21]
	v_cndmask_b32_e64 v148, v157, 0, s[22:23]
	v_cvt_pk_bf16_f32 v147, v147, v148
	v_add_u32_e32 v148, v233, v235
	ds_write_b64 v148, v[146:147]

; #define GAS __attribute__((address_space(1)))
; __device__ __forceinline__ unsigned pk2(float lo, float hi) { const f32x2_t v = {lo, hi}; const bf16x2_t b = __builtin_convertvector(v, bf16x2_t); return __builtin_bit_cast(unsigned, b); }
; #define MX_MFMA(a, b, c) __builtin_amdgcn_mfma_f32_16x16x32_bf16((a), (b), (c), 0, 0, 0)
; #define MX_BAR() do { asm volatile("s_waitcnt lgkmcnt(0)" ::: "memory"); __builtin_amdgcn_s_barrier(); if (MXP_BAR > 1) __builtin_amdgcn_s_barrier(); asm volatile("" ::: "memory"); } while (0)
; __device__ __forceinline__ void mixer_hg2(const Args& a, Frame& F, bool ctx_out) {
;     ...
;             MX_BAR();
;             if (do_out) {
;                 const mx_bf16x8 bp0 = frag_row8(L + O_P, nq0, 0, lane), bp1 = frag_row8(L + O_P, nq0, 32, lane);
; #pragma unroll
;                 for (int te = 0; te < 2; ++te) { vo[te][0] = frag_row8(L + O_VT, 32 * cg + 16 * te, 0, lane); vo[te][1] = frag_row8(L + O_VT, 32 * cg + 16 * te, 32, lane); }
;                 __builtin_amdgcn_sched_barrier(0);
;                 f32x4 oa = ZERO4, ob = oa;
;                 oa = MX_MFMA(vo[0][0], bp0, oa); ob = MX_MFMA(vo[1][0], bp0, ob);
; #pragma unroll
;                 for (int ks = 0; ks < KS; ++ks) { oa = MX_MFMA(st[0][ks], aq[ks], oa); ob = MX_MFMA(st[1][ks], aq[ks], ob); }
;                 oa = MX_MFMA(vo[0][1], bp1, oa); ob = MX_MFMA(vo[1][1], bp1, ob);
;                 bf16* op = O + (size_t)(rlo + (dir ? 63 - (nq0 + i) : (nq0 + i))) * D + h * HD + eb * 64 + 32 * cg + 4 * g;
;                 v2u wa, wb; wa.x = pk2(oa[0], oa[1]); wa.y = pk2(oa[2], oa[3]); wb.x = pk2(ob[0], ob[1]); wb.y = pk2(ob[2], ob[3]);
;                 *(GAS v2u*)(op) = wa; *(GAS v2u*)(op + 16) = wb;
;             }
;             MX_BAR();
.LBB0_520:
	s_waitcnt lgkmcnt(0)
	s_barrier
	s_and_b64 vcc, exec, s[26:27]
	s_cbranch_vccnz .LBB0_522
	v_sub_co_u32_e64 v146, s[26:27], s31, 4
	s_and_b64 s[34:35], s[24:25], exec
	v_readfirstlane_b32 s34, v146
	v_add_u32_e32 v150, v233, v232
	v_add_u32_e32 v166, v243, v232
	s_cselect_b32 s34, s34, s30
	ds_read_b128 v[146:149], v150
	ds_read_b128 v[150:153], v150 offset:64
	ds_read_b128 v[154:157], v166 offset:55296
	ds_read_b128 v[158:161], v166 offset:55360
	ds_read_b128 v[162:165], v166 offset:57856
	ds_read_b128 v[166:169], v166 offset:57920
	s_lshl_b32 s37, s34, 6
	s_sub_i32 s30, s30, 64
	s_and_b64 s[34:35], s[24:25], exec
	s_cselect_b32 s30, s31, s30
	s_lshl_b32 s30, s30, 6
	s_add_i32 s30, s30, s33
	s_add_i32 s37, s37, s7
	s_and_b64 s[26:27], s[26:27], exec
	s_cselect_b32 s26, s30, s37
	s_waitcnt lgkmcnt(3)
	v_mfma_f32_16x16x32_bf16 v[154:157], v[154:157], v[146:149], v[2:5]
	s_waitcnt lgkmcnt(1)
	v_mfma_f32_16x16x32_bf16 v[146:149], v[162:165], v[146:149], v[2:5]
	v_add_u32_e32 v162, s26, v248
	v_ashrrev_i32_e32 v163, 31, v162
	v_lshlrev_b64 v[162:163], 12, v[162:163]
	v_mfma_f32_16x16x32_bf16 v[154:157], v[62:65], v[14:17], v[154:157]
	v_mfma_f32_16x16x32_bf16 v[146:149], v[78:81], v[14:17], v[146:149]
	v_mfma_f32_16x16x32_bf16 v[154:157], v[66:69], v[18:21], v[154:157]
	v_mfma_f32_16x16x32_bf16 v[146:149], v[82:85], v[18:21], v[146:149]
	v_mfma_f32_16x16x32_bf16 v[154:157], v[70:73], v[22:25], v[154:157]
	v_mfma_f32_16x16x32_bf16 v[146:149], v[86:89], v[22:25], v[146:149]
	v_mfma_f32_16x16x32_bf16 v[154:157], v[74:77], v[42:45], v[154:157]
	v_mfma_f32_16x16x32_bf16 v[146:149], v[90:93], v[42:45], v[146:149]
	v_mfma_f32_16x16x32_bf16 v[154:157], v[158:161], v[150:153], v[154:157]
	v_lshl_add_u64 v[158:159], v[194:195], 0, v[162:163]
	s_waitcnt lgkmcnt(0)
	v_mfma_f32_16x16x32_bf16 v[146:149], v[166:169], v[150:153], v[146:149]
	s_nop 4
	v_cvt_pk_bf16_f32 v154, v154, v155
	v_cvt_pk_bf16_f32 v155, v156, v157
	s_nop 0
	v_cvt_pk_bf16_f32 v146, v146, v147
	v_cvt_pk_bf16_f32 v147, v148, v149
	global_store_dwordx2 v[158:159], v[154:155], off
	global_store_dwordx2 v[158:159], v[146:147], off offset:32
